# mixers queue: last 32 groups issued longest unit type first, short retention-sample tail
# baseline (speedup 1.0000x reference)
; __device__ __forceinline__ void phase_mixers(const Params& p, LAS unsigned char* lds, int rep) {
;     ...
;     const int u = (int)__builtin_amdgcn_readfirstlane(*slot);
;     if (u >= 2304) break;
;     if (threadIdx.x == 0) nxt = atomicAdd(ctr, 1u);
;     if (u < 128) mix_ret_prompt(p, lds, u);
;     else {
;       const int v = u - 128, g = v / 17, s = v % 17;
;       if (s < 8) mix_ret_sample(p, lds, g * 8 + s);
;       else if (s < 12) mix_ma_sample(p, lds, g * 4 + (s - 8));
;       else if (s < 14) mix_ma_prompt(p, lds, g * 2 + (s - 12));
;       else if (s < 16) mix_sg_prompt(p, lds, g * 2 + (s - 14));
;       else mix_sg_sample(p, lds, g);
.LBB0_193:
	s_add_i32 s29, s42, 0xff80
	s_and_b32 s29, s29, 0xffff
	s_cmpk_lt_u32 s29, 0x660
	s_cbranch_scc1 .Lq_done
	s_cmpk_lt_u32 s29, 0x780
	s_cbranch_scc0 .Lq_tail
	s_sub_i32 s29, s29, 0x660
	s_cmpk_lt_u32 s29, 32
	s_cbranch_scc0 .Lq_m1
	s_mul_i32 s29, s29, 17
	s_add_i32 s29, s29, 0x670
	s_branch .Lq_done
.Lq_m1:
	s_cmpk_lt_u32 s29, 160
	s_cbranch_scc0 .Lq_m2
	s_sub_i32 s29, s29, 32
	s_lshr_b32 s34, s29, 2
	s_and_b32 s35, s29, 3
	s_mul_i32 s34, s34, 17
	s_add_i32 s29, s34, s35
	s_add_i32 s29, s29, 0x668
	s_branch .Lq_done
.Lq_m2:
	s_cmpk_lt_u32 s29, 224
	s_cbranch_scc0 .Lq_m3
	s_sub_i32 s29, s29, 160
	s_lshr_b32 s34, s29, 1
	s_and_b32 s35, s29, 1
	s_mul_i32 s34, s34, 17
	s_add_i32 s29, s34, s35
	s_add_i32 s29, s29, 0x66c
	s_branch .Lq_done
.Lq_m3:
	s_sub_i32 s29, s29, 224
	s_lshr_b32 s34, s29, 1
	s_and_b32 s35, s29, 1
	s_mul_i32 s34, s34, 17
	s_add_i32 s29, s34, s35
	s_add_i32 s29, s29, 0x66e
	s_branch .Lq_done
